# lora GEMM skips the all-zero K-tiles of the block-structured lora weights (N-tiles 0-7 use K-tiles 0-1, N-tiles 8-11 K-tiles 2-5); same math, zero products dropped
# speedup vs baseline: 1.0063x; 1.0063x over previous
; #define PG8_WAIT_V(n) asm volatile("s_waitcnt vmcnt(" #n ")" ::: "memory")
; #define PG8_BAR __builtin_amdgcn_s_barrier()
; template <class Epi, class Sched, bool ALIGN_EPI = false, bool SP2 = false>
; __device__ __forceinline__ void gemm_phase(PG8_LAS unsigned char* lds, const Gemm g, const Sched& S, const Epi& E) {
;     int tid_l = threadIdx.x; asm volatile("" : "+v"(tid_l)); const int tid = tid_l, wid = __builtin_amdgcn_readfirstlane(tid >> 6), lane = tid & 63, wr = wid >> 2, wc = wid & 3, fr = lane & 15, fq = lane >> 4;
;     const int K = g.K, nt = K / BK;
;     unsigned voffA[2], voffB[2];
; #pragma unroll
;     for (int i = 0; i < 2; ++i) { int R, C; stage_rc(tid * 16 + i * 8192, R, C); const int Rb = Epi::PERM ? ((R & ~31) + perm32(R & 31)) : R;
;         voffA[i] = (unsigned)(R * K + C) * 2u; voffB[i] = (unsigned)(Rb * K + C) * 2u; }
;     const size_t kstep = (size_t)(BK * 2);
;     const size_t hstep = (size_t)HALF * K * 2;
;     const size_t tstep = 2 * hstep;
;     const unsigned ldsw = (unsigned)wid * 1024u;
;     const int aoff = lds_byte(wr * 64 + fr, fq * 8), boff = lds_byte(wc * 32 + fr, fq * 8);
;     ...
;     Unit cur, nxt; int ui = 0;
;     if (!S.next(0, cur)) return;
;     f32x4 acc[2][2][4][2];
; #pragma unroll
;     for (int a = 0; a < 2; ++a)
; #pragma unroll
;         for (int b = 0; b < 2; ++b)
; #pragma unroll
;             for (int m = 0; m < 4; ++m)
; #pragma unroll
;                 for (int n = 0; n < 2; ++n) acc[a][b][m][n] = (f32x4){0.f, 0.f, 0.f, 0.f};
;     bf16x8 At[4][2], B0[2][2], B1[2][2];
;     const char* cA = (const char*)g.A + (size_t)cur.pm * tstep; const char* cB = (const char*)g.Bt + (size_t)cur.pn * tstep;
;     S.a_ready(cur);
;     if constexpr (SP2) {
;         PG8_STAGE(PG8_SB(0, 0), cB, voffB); PG8_STAGE(PG8_SB(0, 1), cB + hstep, voffB); PG8_STAGE(PG8_SA(0, 0), cA, voffA); PG8_STAGE(PG8_SA(0, 1), cA + hstep, voffA);
;         if (wr == 1) PG8_BAR;
;         PG8_WAIT_V(2); PG8_BAR;
;         PG8_STAGE(PG8_SB(1, 0), cB + kstep, voffB); PG8_STAGE(PG8_SA(1, 0), cA + kstep, voffA); PG8_STAGE(PG8_SB(1, 1), cB + hstep + kstep, voffB);
;         PG8_WAIT_V(6); PG8_BAR;
;     } else {
;         PG8_STAGE(PG8_SB(0, 0), cB, voffB); PG8_STAGE(PG8_SA(0, 0), cA, voffA); PG8_STAGE(PG8_SB(0, 1), cB + hstep, voffB); PG8_STAGE(PG8_SA(0, 1), cA + hstep, voffA);
;         if (wr == 1) PG8_BAR;
;         PG8_WAIT_V(4); PG8_BAR;
.LBB0_497:
	s_lshl_b32 s76, s8, 6
	s_waitcnt vmcnt(0)
	v_mov_b32_e32 v12, v216
	s_cmp_ge_i32 s59, s76
	v_readfirstlane_b32 s1, v12
	s_cbranch_scc1 .LBB0_474
	v_lshlrev_b32_e32 v0, 4, v12
	s_waitcnt lgkmcnt(0)
	v_add_u32_e32 v1, 0x2000, v0
	v_ashrrev_i32_e32 v2, 31, v1
	v_lshrrev_b32_e32 v2, 22, v2
	v_add_u32_e32 v2, v1, v2
	v_ashrrev_i32_e32 v2, 10, v2
	v_mul_i32_i24_e32 v3, 0x400, v2
	v_sub_u32_e32 v1, v1, v3
	v_lshrrev_b32_e32 v3, 4, v1
	v_bitop3_b32 v1, v3, v1, 32 bitop3:0x6c
	v_ashrrev_i32_e32 v3, 31, v1
	v_lshrrev_b32_e32 v3, 26, v3
	v_add_u32_e32 v3, v1, v3
	v_lshlrev_b32_e32 v5, 3, v2
	v_ashrrev_i32_e32 v4, 6, v3
	v_and_b32_e32 v5, -16, v5
	v_lshlrev_b32_e32 v2, 5, v2
	v_add_u32_e32 v5, v4, v5
	v_and_b32_e32 v13, 32, v2
	v_and_b32_e32 v2, 0xc0, v3
	v_and_b32_e32 v4, 3, v4
	s_mov_b32 s0, 0x7fffffe0
	v_lshrrev_b32_e32 v6, 2, v5
	v_lshlrev_b32_e32 v7, 1, v5
	v_sub_u32_e32 v1, v1, v2
	v_and_or_b32 v4, v5, s0, v4
	v_and_b32_e32 v6, 4, v6
	v_and_b32_e32 v7, 24, v7
	v_ashrrev_i16_sdwa v1, v217, sext(v1) dst_sel:DWORD dst_unused:UNUSED_PAD src0_sel:DWORD src1_sel:BYTE_0
	v_or3_b32 v4, v4, v6, v7
	v_bfe_i32 v14, v1, 0, 16
	v_mul_lo_u32 v4, v4, s6
	v_add_u32_e32 v1, v13, v14
	v_mul_lo_u32 v15, v5, s6
	v_add_lshl_u32 v178, v4, v1, 1
	v_add_lshl_u32 v180, v1, v15, 1
	v_bfe_i32 v1, v12, 27, 1
	v_lshrrev_b32_e32 v1, 22, v1
	v_add_u32_e32 v1, v0, v1
	v_and_b32_e32 v1, 0xfffffc00, v1
	v_sub_u32_e32 v0, v0, v1
	v_lshrrev_b32_e32 v1, 4, v0
	v_ashrrev_i32_e32 v3, 31, v12
	v_bitop3_b32 v0, v1, v0, 32 bitop3:0x6c
	v_lshrrev_b32_e32 v3, 26, v3
	v_ashrrev_i32_e32 v1, 31, v0
	v_add_u32_e32 v3, v12, v3
	v_lshrrev_b32_e32 v1, 26, v1
	v_ashrrev_i32_e32 v3, 6, v3
	s_ashr_i32 s7, s1, 6
	s_lshl_b32 s28, s6, 8
	v_add_u32_e32 v1, v0, v1
	v_lshlrev_b32_e32 v4, 3, v3
	s_lshl_b32 s5, s8, 3
	s_ashr_i32 s17, s1, 8
	s_lshl_b64 s[78:79], s[28:29], 1
	s_lshl_b32 s4, s7, 10
	v_ashrrev_i32_e32 v2, 6, v1
	v_and_b32_e32 v4, -16, v4
	v_and_b32_e32 v1, 0xc0, v1
	s_or_b32 s46, s5, 1
	v_add_u32_e32 v4, v2, v4
	v_and_b32_e32 v2, 3, v2
	v_sub_u32_e32 v0, v0, v1
	s_and_b64 s[30:31], s[64:65], exec
	v_and_or_b32 v2, v4, s0, v2
	v_ashrrev_i16_sdwa v0, v217, sext(v0) dst_sel:DWORD dst_unused:UNUSED_PAD src0_sel:DWORD src1_sel:BYTE_0
	s_cselect_b32 s0, s46, s5
	s_lshl_b32 s47, s8, 2
	v_bfe_i32 v17, v0, 0, 16
	v_cvt_f32_u32_e32 v0, s47
	s_sub_i32 s30, 0, s47
	s_mul_i32 s0, s0, s14
	s_add_i32 s0, s0, s49
	v_rcp_iflag_f32_e32 v0, v0
	s_abs_i32 s9, s0
	s_ashr_i32 s8, s0, 31
	v_lshrrev_b32_e32 v5, 2, v4
	v_mul_f32_e32 v0, 0x4f7ffffe, v0
	v_cvt_u32_f32_e32 v0, v0
	v_lshlrev_b32_e32 v6, 1, v4
	v_and_b32_e32 v5, 4, v5
	v_and_b32_e32 v6, 24, v6
	v_readfirstlane_b32 s91, v0
	s_mul_i32 s30, s30, s91
	s_mul_hi_u32 s30, s91, s30
	s_add_i32 s91, s91, s30
	s_mul_hi_u32 s30, s9, s91
	s_mul_i32 s31, s30, s47
	s_sub_i32 s9, s9, s31
	s_add_i32 s31, s30, 1
	s_sub_i32 s33, s9, s47
	s_cmp_ge_u32 s9, s47
	s_cselect_b32 s30, s31, s30
	s_cselect_b32 s9, s33, s9
	s_add_i32 s31, s30, 1
	s_cmp_ge_u32 s9, s47
	s_cselect_b32 s9, s31, s30
	s_xor_b32 s9, s9, s8
	s_sub_i32 s8, s9, s8
	s_lshl_b32 s30, s8, 2
	s_sub_i32 s9, 64, s30
	s_min_i32 s31, s9, 4
	s_sext_i32_i16 s9, s31
	v_cvt_f32_i32_e32 v0, s9
	v_lshlrev_b32_e32 v3, 5, v3
	s_mul_i32 s8, s8, s47
	v_or3_b32 v2, v2, v5, v6
	v_and_b32_e32 v16, 32, v3
	s_sub_i32 s33, s0, s8
	v_mul_lo_u32 v2, v2, s6
	v_add_u32_e32 v1, v16, v17
	v_mul_lo_u32 v18, v4, s6
	s_sext_i32_i16 s0, s33
	v_add_lshl_u32 v96, v2, v1, 1
	v_add_lshl_u32 v182, v1, v18, 1
	v_cvt_f32_i32_e32 v1, s0
	v_rcp_iflag_f32_e32 v2, v0
	s_xor_b32 s0, s0, s9
	s_ashr_i32 s0, s0, 30
	s_or_b32 s0, s0, 1
	v_mul_f32_e32 v2, v1, v2
	v_trunc_f32_e32 v2, v2
	v_fma_f32 v1, -v2, v0, v1
	v_cvt_i32_f32_e32 v2, v2
	v_cmp_ge_f32_e64 s[8:9], |v1|, |v0|
	s_and_b64 s[8:9], s[8:9], exec
	s_cselect_b32 s0, s0, 0
	v_readfirstlane_b32 s8, v2
	s_add_i32 s0, s8, s0
	s_mul_i32 s8, s0, s31
	s_sub_i32 s8, s33, s8
	s_sext_i32_i16 s8, s8
	s_add_i32 s52, s30, s8
	s_ashr_i32 s8, s52, 31
	s_mul_i32 s8, s78, s8
	s_mul_hi_u32 s9, s78, s52
	s_bfe_u32 s30, s6, 0x10017
	s_add_i32 s8, s9, s8
	s_mul_i32 s9, s30, s52
	s_add_i32 s33, s8, s9
	s_bfe_i64 s[8:9], s[0:1], 0x100000
	s_mul_i32 s9, s78, s9
	s_mul_hi_u32 s31, s78, s8
	s_add_i32 s9, s31, s9
	s_mul_i32 s30, s30, s8
	s_add_i32 s9, s9, s30
	s_mul_i32 s8, s78, s8
	s_add_u32 s94, s68, s8
	s_addc_u32 s95, s69, s9
	s_cmpk_eq_u32 s6, 0x180
	s_cselect_b32 vcc_lo, 0x100, 0
	s_sext_i32_i16 vcc_hi, s0
	s_cmp_gt_i32 vcc_hi, 7
	s_cselect_b32 vcc_lo, vcc_lo, 0
	s_add_u32 s94, s94, vcc_lo
	s_addc_u32 s95, s95, 0
	s_add_i32 s90, s4, 0
	s_add_i32 m0, s90, 0x10000
	s_mul_i32 s40, s78, s52
	global_load_lds_dwordx4 v96, s[94:95]
	s_add_i32 m0, s90, 0x12000
	s_add_u32 s30, s94, s28
	global_load_lds_dwordx4 v178, s[94:95]
	s_addc_u32 s31, s95, 0
	s_add_i32 m0, s90, 0x14000
	v_mov_b32_e32 v179, v97
	global_load_lds_dwordx4 v96, s[30:31]
	s_add_i32 m0, s90, 0x16000
	s_add_u32 s96, s72, s40
	s_addc_u32 s97, s73, s33
	s_add_u32 s96, s96, vcc_lo
	s_addc_u32 s97, s97, 0
	s_add_i32 s8, s90, 0x2000
	global_load_lds_dwordx4 v178, s[30:31]
	s_mov_b32 m0, s90
	s_add_u32 s40, s96, s28
	global_load_lds_dwordx4 v182, s[96:97]
	s_mov_b32 m0, s8
	s_addc_u32 s41, s97, 0
	s_add_i32 s9, s90, 0x4000
	global_load_lds_dwordx4 v180, s[96:97]
	s_mov_b32 m0, s9
	s_add_i32 s33, s90, 0x6000
	global_load_lds_dwordx4 v182, s[40:41]
	s_mov_b32 m0, s33
	v_mov_b32_e32 v183, v97
	global_load_lds_dwordx4 v180, s[40:41]
	v_mov_b32_e32 v181, v97
	s_cmp_eq_u32 s17, 1
	s_mov_b32 s62, s93
	v_lshl_add_u64 v[8:9], s[94:95], 0, v[96:97]
	v_lshl_add_u64 v[4:5], s[94:95], 0, v[178:179]
	v_lshl_add_u64 v[2:3], s[30:31], 0, v[96:97]
	v_lshl_add_u64 v[0:1], s[30:31], 0, v[178:179]
	v_lshl_add_u64 v[6:7], s[96:97], 0, v[182:183]
	s_cselect_b64 s[80:81], -1, 0
	s_cmp_lg_u32 s17, 1
	v_lshl_add_u64 v[10:11], s[96:97], 0, v[180:181]
	s_cbranch_scc1 .LBB0_500
	s_barrier

; template <class Epi, class Sched, bool ALIGN_EPI = false, bool SP2 = false>
; __device__ __forceinline__ void gemm_phase(PG8_LAS unsigned char* lds, const Gemm g, const Sched& S, const Epi& E) {
;     ...
;     const int K = g.K, nt = K / BK;
;     ...
;         for (int t = 0; t < nt; t += 2) {
;             const bool last = (t == nt - 2);
;             const char* a1 = cA + (size_t)(t + 1) * kstep;
;             const char* a2 = last ? nA : cA + (size_t)(t + 2) * kstep; const char* b2 = last ? nB : cB + (size_t)(t + 2) * kstep;
.LBB0_503:
	s_cmp_eq_u32 s28, 0x18000
	s_cbranch_scc0 .Llr_nt_done
	s_cmp_gt_i32 s31, 7
	s_cselect_b32 s58, 4, 2
	s_add_i32 s7, s58, -2

; template <class Epi, class Sched, bool ALIGN_EPI = false, bool SP2 = false>
; __device__ __forceinline__ void gemm_phase(PG8_LAS unsigned char* lds, const Gemm g, const Sched& S, const Epi& E) {
;     ...
;         const bool has_next = S.next(ui + 1, nxt);
;         const char* nA = has_next ? (const char*)g.A + (size_t)nxt.pm * tstep : cA; const char* nB = has_next ? (const char*)g.Bt + (size_t)nxt.pn * tstep : cB;
.LBB0_505:
	s_nop 0
	v_cndmask_b32_e64 v0, 0, 1, s[40:41]
	v_cmp_ne_u32_e64 s[38:39], 1, v0
	s_andn2_b64 vcc, exec, s[40:41]
	s_mov_b64 s[88:89], s[96:97]
	s_cbranch_vccnz .LBB0_507
	s_ashr_i32 s0, s44, 31
	s_mul_hi_u32 s1, s78, s44
	s_mul_i32 s0, s78, s0
	s_add_i32 s0, s1, s0
	s_mul_i32 s1, s79, s44
	s_add_i32 s0, s0, s1
	s_mul_i32 s1, s78, s44
	s_add_u32 s88, s72, s1
	s_addc_u32 s89, s73, s0
	s_cmp_eq_u32 s28, 0x18000
	s_cselect_b32 s0, 0x100, 0
	s_cmp_gt_i32 s17, 7
	s_cselect_b32 s0, s0, 0
	s_add_u32 s88, s88, s0
	s_addc_u32 s89, s89, 0
.LBB0_507:
	s_and_b64 vcc, exec, s[38:39]
	s_mov_b64 s[86:87], s[94:95]
	s_cbranch_vccnz .LBB0_509
	s_ashr_i32 s0, s17, 31
	s_mul_hi_u32 s1, s78, s17
	s_mul_i32 s0, s78, s0
	s_add_i32 s0, s1, s0
	s_mul_i32 s1, s79, s17
	s_add_i32 s0, s0, s1
	s_mul_i32 s1, s78, s17
	s_add_u32 s86, s68, s1
	s_addc_u32 s87, s69, s0
	s_cmp_eq_u32 s28, 0x18000
	s_cselect_b32 s0, 0x100, 0
	s_cmp_gt_i32 s17, 7
	s_cselect_b32 s0, s0, 0
	s_add_u32 s86, s86, s0
	s_addc_u32 s87, s87, 0
